# v78 + P1 x pass: the 15 spare sum-of-squares partials of a row zero-filled as one 60-byte run instead of 15 stores 48 KB apart
# speedup vs baseline: 1.0118x; 1.0010x over previous
.LBB0_169:
	s_cmpk_gt_i32 s61, 0x187
	s_mov_b64 s[6:7], -1
	s_cbranch_scc0 .LBB0_177
	v_mov_b32_e32 v4, v155
	s_lshl_b32 s6, s61, 3
	s_addk_i32 s6, 0xf3c0
	v_ashrrev_i32_e32 v0, 6, v4
	v_add_u32_e32 v0, s6, v0
	v_cmp_gt_i32_e32 vcc, s48, v0
	v_cmp_lt_i32_e64 s[6:7], s49, v0
	v_add_u32_e32 v8, 0xfffff000, v0
	s_and_saveexec_b64 s[30:31], s[6:7]
	s_xor_b64 s[6:7], exec, s[30:31]
	v_lshlrev_b64 v[2:3], 12, v[8:9]
	v_lshl_add_u64 v[2:3], s[14:15], 0, v[2:3]
	v_mov_b32_e32 v1, v9
	s_andn2_saveexec_b64 s[6:7], s[6:7]
	v_ashrrev_i32_e32 v1, 31, v0
	v_lshlrev_b64 v[2:3], 12, v[0:1]
	v_lshl_add_u64 v[2:3], s[12:13], 0, v[2:3]
	s_or_b64 exec, exec, s[6:7]
	v_lshrrev_b32_e32 v5, 10, v8
	v_add_u32_e32 v5, 1, v5
	v_cndmask_b32_e64 v5, v5, 0, vcc
	v_mov_b64_e32 v[6:7], s[10:11]
	v_and_b32_e32 v4, 63, v4
	v_mad_u64_u32 v[6:7], s[6:7], v5, s52, v[6:7]
	v_lshl_add_u64 v[6:7], v[6:7], 0, s[28:29]
	v_lshlrev_b32_e32 v8, 4, v4
	v_lshl_add_u64 v[2:3], v[2:3], 0, v[8:9]
	v_lshl_add_u64 v[18:19], v[6:7], 0, v[8:9]
	global_load_dwordx4 v[10:13], v[2:3], off nt
	global_load_dwordx4 v[14:17], v8, s[2:3]
	v_lshlrev_b64 v[22:23], 12, v[0:1]
	global_load_dwordx4 v[18:21], v[18:19], off
	v_lshlrev_b64 v[24:25], 11, v[0:1]
	v_mov_b32_e32 v27, v9
	v_lshl_add_u64 v[22:23], s[8:9], 0, v[22:23]
	v_lshl_add_u64 v[24:25], s[16:17], 0, v[24:25]
	v_lshlrev_b32_e32 v26, 3, v4
	v_mov_b32_e32 v29, v9
	v_lshl_add_u64 v[34:35], v[22:23], 0, v[8:9]
	v_lshl_add_u64 v[36:37], v[24:25], 0, v[26:27]
	v_or_b32_e32 v28, 0x400, v8
	v_lshl_add_u64 v[22:23], v[6:7], 0, v[28:29]
	v_or_b32_e32 v26, 0x800, v8
	v_lshl_add_u64 v[26:27], v[6:7], 0, v[26:27]
	v_cmp_gt_u32_e32 vcc, 16, v4
	s_waitcnt vmcnt(2)
	global_store_dwordx4 v[34:35], v[10:13], off
	s_waitcnt vmcnt(2)
	v_pk_mul_f32 v[16:17], v[12:13], v[16:17]
	v_pk_mul_f32 v[14:15], v[10:11], v[14:15]
	s_waitcnt vmcnt(1)
	v_pk_add_f32 v[18:19], v[18:19], 1.0 op_sel_hi:[1,0]
	v_pk_add_f32 v[20:21], v[20:21], 1.0 op_sel_hi:[1,0]
	v_pk_mul_f32 v[14:15], v[14:15], v[18:19]
	v_pk_mul_f32 v[16:17], v[16:17], v[20:21]
	v_cvt_pk_bf16_f32 v14, v14, v15
	v_cvt_pk_bf16_f32 v15, v16, v17
	global_store_dwordx2 v[36:37], v[14:15], off
	global_load_dwordx4 v[14:17], v[2:3], off offset:1024 nt
	s_nop 0
	global_load_dwordx4 v[18:21], v8, s[2:3] offset:1024
	s_waitcnt vmcnt(0)
	v_pk_mul_f32 v[20:21], v[16:17], v[20:21]
	global_load_dwordx4 v[22:25], v[22:23], off
	v_pk_mul_f32 v[18:19], v[14:15], v[18:19]
	global_store_dwordx4 v[34:35], v[14:17], off offset:1024
	s_waitcnt vmcnt(1)
	v_pk_add_f32 v[22:23], v[22:23], 1.0 op_sel_hi:[1,0]
	v_pk_add_f32 v[24:25], v[24:25], 1.0 op_sel_hi:[1,0]
	v_pk_mul_f32 v[18:19], v[18:19], v[22:23]
	v_pk_mul_f32 v[20:21], v[20:21], v[24:25]
	v_cvt_pk_bf16_f32 v18, v18, v19
	v_cvt_pk_bf16_f32 v19, v20, v21
	global_store_dwordx2 v[36:37], v[18:19], off offset:512
	global_load_dwordx4 v[18:21], v[2:3], off offset:2048 nt
	s_nop 0
	global_load_dwordx4 v[22:25], v8, s[2:3] offset:2048
	s_waitcnt vmcnt(0)
	v_pk_mul_f32 v[24:25], v[20:21], v[24:25]
	global_load_dwordx4 v[26:29], v[26:27], off
	v_pk_mul_f32 v[22:23], v[18:19], v[22:23]
	global_store_dwordx4 v[34:35], v[18:21], off offset:2048
	s_waitcnt vmcnt(1)
	v_pk_add_f32 v[26:27], v[26:27], 1.0 op_sel_hi:[1,0]
	v_pk_add_f32 v[28:29], v[28:29], 1.0 op_sel_hi:[1,0]
	v_pk_mul_f32 v[22:23], v[22:23], v[26:27]
	v_pk_mul_f32 v[24:25], v[24:25], v[28:29]
	v_cvt_pk_bf16_f32 v22, v22, v23
	v_cvt_pk_bf16_f32 v23, v24, v25
	global_store_dwordx2 v[36:37], v[22:23], off offset:1024
	global_load_dwordx4 v[22:25], v[2:3], off offset:3072 nt
	s_nop 0
	global_load_dwordx4 v[26:29], v8, s[2:3] offset:3072
	v_or_b32_e32 v8, 0xc00, v8
	v_lshl_add_u64 v[2:3], v[6:7], 0, v[8:9]
	global_load_dwordx4 v[30:33], v[2:3], off
	v_mul_f32_e32 v2, v11, v11
	v_mul_f32_e32 v3, v15, v15
	v_fmac_f32_e32 v2, v10, v10
	v_fmac_f32_e32 v3, v14, v14
	v_fmac_f32_e32 v2, v12, v12
	v_fmac_f32_e32 v3, v16, v16
	v_fmac_f32_e32 v2, v13, v13
	v_fmac_f32_e32 v3, v17, v17
	v_add_f32_e32 v2, v2, v3
	v_mul_f32_e32 v3, v19, v19
	v_fmac_f32_e32 v3, v18, v18
	v_fmac_f32_e32 v3, v20, v20
	v_fmac_f32_e32 v3, v21, v21
	v_add_f32_e32 v5, v2, v3
	s_waitcnt vmcnt(2)
	v_mul_f32_e32 v8, v23, v23
	v_fmac_f32_e32 v8, v22, v22
	v_fmac_f32_e32 v8, v24, v24
	s_waitcnt vmcnt(1)
	v_pk_mul_f32 v[2:3], v[24:25], v[28:29]
	v_pk_mul_f32 v[6:7], v[22:23], v[26:27]
	s_waitcnt vmcnt(0)
	v_pk_add_f32 v[10:11], v[30:31], 1.0 op_sel_hi:[1,0]
	v_pk_add_f32 v[12:13], v[32:33], 1.0 op_sel_hi:[1,0]
	v_fmac_f32_e32 v8, v25, v25
	v_pk_mul_f32 v[6:7], v[6:7], v[10:11]
	v_pk_mul_f32 v[2:3], v[2:3], v[12:13]
	v_add_f32_e32 v5, v5, v8
	v_cvt_pk_bf16_f32 v6, v6, v7
	v_cvt_pk_bf16_f32 v7, v2, v3
	v_add_f32_dpp v2, v5, v5 quad_perm:[1,0,3,2] row_mask:0xf bank_mask:0xf bound_ctrl:1
	global_store_dwordx4 v[34:35], v[22:25], off offset:3072
	global_store_dwordx2 v[36:37], v[6:7], off offset:1536
	v_add_f32_dpp v2, v2, v2 quad_perm:[2,3,0,1] row_mask:0xf bank_mask:0xf bound_ctrl:1
	s_nop 1
	v_add_f32_dpp v2, v2, v2 row_half_mirror row_mask:0xf bank_mask:0xf bound_ctrl:1
	s_nop 1
	v_add_f32_dpp v2, v2, v2 row_mirror row_mask:0xf bank_mask:0xf bound_ctrl:1
	v_mov_b32_e32 v3, v2
	s_nop 1
	v_permlane16_swap_b32_e32 v2, v3
	v_add_f32_e32 v2, v2, v3
	v_mov_b32_e32 v3, v2
	s_nop 1
	v_permlane32_swap_b32_e32 v2, v3
	s_and_saveexec_b64 s[6:7], vcc
	s_cbranch_execz .LBB0_176
	v_add_f32_e32 v2, v2, v3
	v_cmp_eq_u32_e32 vcc, 0, v4
	s_nop 1
	v_cndmask_b32_e32 v5, 0, v2, vcc
	v_mul_u32_u24_e32 v8, 15, v0
	v_add_u32_e32 v8, v8, v4
	v_add_u32_e32 v8, 0x2fff, v8
	v_cndmask_b32_e32 v8, v8, v0, vcc
	v_lshlrev_b32_e32 v8, 2, v8
	v_lshl_add_u64 v[0:1], s[18:19], 0, v[8:9]
	global_store_dword v[0:1], v5, off
